# queue claim prefetch also for latent Hyena units (issued at the start of the second filter order)
# baseline (speedup 1.0000x reference)
.LBB0_1263:
	s_cmp_lg_u64 s[6:7], 0
	s_cbranch_scc1 .Lqe4
	s_mov_b64 s[98:99], exec
	s_mov_b64 exec, s[4:5]
	s_cbranch_execz .Lqp4
	v_readlane_b32 s16, v252, 23
	v_readlane_b32 s17, v252, 24
	s_nop 1
	v_mov_b64_e32 v[254:255], s[16:17]
	global_atomic_add v253, v[254:255], v177, off sc0
.Lqp4:
	s_mov_b64 exec, s[98:99]
	s_mov_b32 s32, 1
.Lqe4:
	s_and_b64 s[16:17], s[6:7], exec
	s_mov_b32 s16, 0xd7f2000
	s_cselect_b32 s16, s16, 0xddf2000
	s_add_u32 s16, s8, s16
	s_addc_u32 s17, s9, 0
	v_lshl_add_u64 v[136:137], v[20:21], 1, s[16:17]
	s_mov_b64 s[16:17], 0x3000
	v_lshl_add_u64 v[136:137], v[136:137], 0, s[16:17]
	global_load_dwordx2 v[140:141], v[136:137], off offset:-4096
	global_load_dwordx2 v[142:143], v[136:137], off
	v_lshl_add_u64 v[138:139], v[136:137], 0, s[52:53]
	global_load_dwordx2 v[144:145], v[138:139], off offset:-4096
	global_load_dwordx2 v[146:147], v[138:139], off
	s_andn2_b64 vcc, exec, s[10:11]
	v_mov_b32_e32 v7, v0
	v_mov_b32_e32 v6, v0
	v_mov_b32_e32 v5, v0
	v_mov_b32_e32 v4, v0
	v_mov_b32_e32 v11, v0
	v_mov_b32_e32 v10, v0
	v_mov_b32_e32 v9, v0
	v_mov_b32_e32 v8, v0
	v_mov_b32_e32 v15, v0
	v_mov_b32_e32 v14, v0
	v_mov_b32_e32 v13, v0
	v_mov_b32_e32 v12, v0
	v_mov_b32_e32 v19, v0
	v_mov_b32_e32 v18, v0
	v_mov_b32_e32 v17, v0
	v_mov_b32_e32 v16, v0
	s_cbranch_vccnz .LBB0_1266
	v_or_b32_e32 v4, s12, v36
	s_and_b64 s[12:13], s[6:7], exec
	s_movk_i32 s12, 0x5380
	s_cselect_b32 s12, s12, 0xa380
	s_movk_i32 s13, 0x1060
	v_mad_u32_u24 v30, v4, s13, v38
	v_add_u32_e32 v31, s12, v39
	s_mov_b32 s12, s18
	v_mov_b32_e32 v16, v0
	v_mov_b32_e32 v17, v0
	v_mov_b32_e32 v18, v0
	v_mov_b32_e32 v19, v0
	v_mov_b32_e32 v12, v0
	v_mov_b32_e32 v13, v0
	v_mov_b32_e32 v14, v0
	v_mov_b32_e32 v15, v0
	v_mov_b32_e32 v8, v0
	v_mov_b32_e32 v9, v0
	v_mov_b32_e32 v10, v0
	v_mov_b32_e32 v11, v0
	v_mov_b32_e32 v4, v0
	v_mov_b32_e32 v5, v0
	v_mov_b32_e32 v6, v0
	v_mov_b32_e32 v7, v0

.LBB0_3020:
	s_cmp_lg_u64 s[6:7], 0
	s_cbranch_scc1 .Lqe9
	s_mov_b64 s[98:99], exec
	s_mov_b64 exec, s[4:5]
	s_cbranch_execz .Lqp9
	v_readlane_b32 s18, v252, 23
	v_readlane_b32 s19, v252, 24
	s_nop 1
	v_mov_b64_e32 v[254:255], s[18:19]
	global_atomic_add v253, v[254:255], v176, off sc0
.Lqp9:
	s_mov_b64 exec, s[98:99]
	s_mov_b32 s32, 1
.Lqe9:
	s_and_b64 s[18:19], s[6:7], exec
	s_mov_b32 s18, 0xd7f2000
	s_cselect_b32 s18, s18, 0xddf2000
	s_add_u32 s18, s8, s18
	s_addc_u32 s19, s9, 0
	v_lshl_add_u64 v[136:137], v[20:21], 1, s[18:19]
	s_mov_b64 s[18:19], 0x3000
	v_lshl_add_u64 v[136:137], v[136:137], 0, s[18:19]
	global_load_dwordx2 v[140:141], v[136:137], off offset:-4096
	global_load_dwordx2 v[142:143], v[136:137], off
	v_lshl_add_u64 v[138:139], v[136:137], 0, s[52:53]
	global_load_dwordx2 v[144:145], v[138:139], off offset:-4096
	global_load_dwordx2 v[146:147], v[138:139], off
	s_andn2_b64 vcc, exec, s[10:11]
	v_mov_b32_e32 v7, v0
	v_mov_b32_e32 v6, v0
	v_mov_b32_e32 v5, v0
	v_mov_b32_e32 v4, v0
	v_mov_b32_e32 v11, v0
	v_mov_b32_e32 v10, v0
	v_mov_b32_e32 v9, v0
	v_mov_b32_e32 v8, v0
	v_mov_b32_e32 v15, v0
	v_mov_b32_e32 v14, v0
	v_mov_b32_e32 v13, v0
	v_mov_b32_e32 v12, v0
	v_mov_b32_e32 v19, v0
	v_mov_b32_e32 v18, v0
	v_mov_b32_e32 v17, v0
	v_mov_b32_e32 v16, v0
	s_cbranch_vccnz .LBB0_3023
	v_or_b32_e32 v4, s12, v36
	s_and_b64 s[12:13], s[6:7], exec
	s_movk_i32 s12, 0x5380
	s_cselect_b32 s12, s12, 0xa380
	s_movk_i32 s13, 0x1060
	v_mad_u32_u24 v30, v4, s13, v38
	v_add_u32_e32 v31, s12, v39
	s_mov_b32 s12, s16
	v_mov_b32_e32 v16, v0
	v_mov_b32_e32 v17, v0
	v_mov_b32_e32 v18, v0
	v_mov_b32_e32 v19, v0
	v_mov_b32_e32 v12, v0
	v_mov_b32_e32 v13, v0
	v_mov_b32_e32 v14, v0
	v_mov_b32_e32 v15, v0
	v_mov_b32_e32 v8, v0
	v_mov_b32_e32 v9, v0
	v_mov_b32_e32 v10, v0
	v_mov_b32_e32 v11, v0
	v_mov_b32_e32 v4, v0
	v_mov_b32_e32 v5, v0
	v_mov_b32_e32 v6, v0
	v_mov_b32_e32 v7, v0
